# speedup vs baseline: 1.0038x; 1.0038x over previous
; __device__ __forceinline__ float silu_f(float v) { return v * sigmoid_f(v); }
; __device__ __forceinline__ u32x4 pack8(const f32x4 a, const f32x4 b) { u32x4 w; w.x = cvt_pk_bf16(a[0], a[1]); w.y = cvt_pk_bf16(a[2], a[3]); w.z = cvt_pk_bf16(b[0], b[1]); w.w = cvt_pk_bf16(b[2], b[3]); return w; }
;     __device__ __forceinline__ void operator()(const f32x4 (&acc)[2][2][4][2], const Unit& u, int wr, int wc, int fr_, int fq_) const {
;     ...
;         const int row0 = u.pm * BM + wr * 64 + fr, colb = u.pn * 128 + wc * 32 + 8 * fq;
; #pragma unroll
;         for (int ai = 0; ai < 2; ++ai)
; #pragma unroll
;             for (int m = 0; m < 4; ++m) { bf16_t* rowp = act + (unsigned)(row0 + ai * HALF + m * 16) * ld + colb;
;                 f32x4 p0, p1; const float rv = 1.0f / sqrtf(ss_read(ss, row0 + ai * HALF + m * 16, fq) * (1.0f / 2048.0f) + 1e-6f);
; #pragma unroll
;                 for (int e = 0; e < 4; ++e) { p0[e] = silu_f(acc[ai][0][m][0][e] * rv) * (acc[ai][1][m][0][e] * rv); p1[e] = silu_f(acc[ai][0][m][1][e] * rv) * (acc[ai][1][m][1][e] * rv); }
;                 *(u32x4*)rowp = pack8(p0, p1); }
.Lrv8_hit:
	s_lshl_b32 s0, s59, 8
	s_add_i32 s0, s0, s39
	v_add_u32_e32 v140, s0, v149
	s_lshl_b32 s0, s2, 7
	s_or_b32 s0, s0, s54
	v_lshl_add_u32 v141, v150, 3, s0
	s_movk_i32 s0, 0x1600
	v_mul_lo_u32 v142, v140, s0
	v_mov_b32_e32 v172, 0xbfb8aa3b
	v_mov_b32_e32 v174, 1.0
	v_add_u32_e32 v142, v142, v141
	v_mov_b32_e32 v143, v193
	s_mov_b32 s0, 0x2c000
	s_mov_b32 s1, 0
	v_lshl_add_u64 v[146:147], v[142:143], 1, s[6:7]
	v_mov_b32_e32 v154, v246
	v_pk_mul_f32 v[124:125], v[124:125], v[154:155] op_sel_hi:[1,0]
	v_pk_mul_f32 v[126:127], v[126:127], v[154:155] op_sel_hi:[1,0]
	v_pk_mul_f32 v[112:113], v[112:113], v[154:155] op_sel_hi:[1,0]
	v_pk_mul_f32 v[114:115], v[114:115], v[154:155] op_sel_hi:[1,0]
	v_pk_mul_f32 v[120:121], v[120:121], v[154:155] op_sel_hi:[1,0]
	v_pk_mul_f32 v[122:123], v[122:123], v[154:155] op_sel_hi:[1,0]
	v_pk_mul_f32 v[116:117], v[116:117], v[154:155] op_sel_hi:[1,0]
	v_pk_mul_f32 v[118:119], v[118:119], v[154:155] op_sel_hi:[1,0]
	v_pk_mul_f32 v[156:157], v[124:125], v[172:173] op_sel_hi:[1,0]
	v_pk_mul_f32 v[158:159], v[126:127], v[172:173] op_sel_hi:[1,0]
	v_pk_mul_f32 v[160:161], v[112:113], v[172:173] op_sel_hi:[1,0]
	v_pk_mul_f32 v[162:163], v[114:115], v[172:173] op_sel_hi:[1,0]
	v_exp_f32_e32 v156, v156
	v_exp_f32_e32 v157, v157
	v_exp_f32_e32 v158, v158
	v_exp_f32_e32 v159, v159
	v_exp_f32_e32 v160, v160
	v_exp_f32_e32 v161, v161
	v_exp_f32_e32 v162, v162
	v_exp_f32_e32 v163, v163
	v_pk_add_f32 v[156:157], v[156:157], v[174:175] op_sel_hi:[1,0]
	v_pk_add_f32 v[158:159], v[158:159], v[174:175] op_sel_hi:[1,0]
	v_pk_add_f32 v[160:161], v[160:161], v[174:175] op_sel_hi:[1,0]
	v_pk_add_f32 v[162:163], v[162:163], v[174:175] op_sel_hi:[1,0]
	v_rcp_f32_e32 v156, v156
	v_rcp_f32_e32 v157, v157
	v_rcp_f32_e32 v158, v158
	v_rcp_f32_e32 v159, v159
	v_rcp_f32_e32 v160, v160
	v_rcp_f32_e32 v161, v161
	v_rcp_f32_e32 v162, v162
	v_rcp_f32_e32 v163, v163
	v_pk_mul_f32 v[156:157], v[124:125], v[156:157]
	v_pk_mul_f32 v[158:159], v[126:127], v[158:159]
	v_pk_mul_f32 v[160:161], v[112:113], v[160:161]
	v_pk_mul_f32 v[162:163], v[114:115], v[162:163]
	v_pk_mul_f32 v[156:157], v[120:121], v[156:157]
	v_pk_mul_f32 v[158:159], v[122:123], v[158:159]
	v_pk_mul_f32 v[160:161], v[116:117], v[160:161]
	v_pk_mul_f32 v[162:163], v[118:119], v[162:163]
	v_cvt_pk_bf16_f32 v164, v156, v157
	v_cvt_pk_bf16_f32 v165, v158, v159
	v_cvt_pk_bf16_f32 v166, v160, v161
	v_cvt_pk_bf16_f32 v167, v162, v163
	global_store_dwordx4 v[146:147], v[164:167], off
	v_lshl_add_u64 v[144:145], v[146:147], 0, s[0:1]
	v_mov_b32_e32 v154, v247
	v_pk_mul_f32 v[108:109], v[108:109], v[154:155] op_sel_hi:[1,0]
	v_pk_mul_f32 v[110:111], v[110:111], v[154:155] op_sel_hi:[1,0]
	v_pk_mul_f32 v[100:101], v[100:101], v[154:155] op_sel_hi:[1,0]
	v_pk_mul_f32 v[102:103], v[102:103], v[154:155] op_sel_hi:[1,0]
	v_pk_mul_f32 v[104:105], v[104:105], v[154:155] op_sel_hi:[1,0]
	v_pk_mul_f32 v[106:107], v[106:107], v[154:155] op_sel_hi:[1,0]
	v_pk_mul_f32 v[96:97], v[96:97], v[154:155] op_sel_hi:[1,0]
	v_pk_mul_f32 v[98:99], v[98:99], v[154:155] op_sel_hi:[1,0]
	v_pk_mul_f32 v[156:157], v[108:109], v[172:173] op_sel_hi:[1,0]
	v_pk_mul_f32 v[158:159], v[110:111], v[172:173] op_sel_hi:[1,0]
	v_pk_mul_f32 v[160:161], v[100:101], v[172:173] op_sel_hi:[1,0]
	v_pk_mul_f32 v[162:163], v[102:103], v[172:173] op_sel_hi:[1,0]
	v_exp_f32_e32 v156, v156
	v_exp_f32_e32 v157, v157
	v_exp_f32_e32 v158, v158
	v_exp_f32_e32 v159, v159
	v_exp_f32_e32 v160, v160
	v_exp_f32_e32 v161, v161
	v_exp_f32_e32 v162, v162
	v_exp_f32_e32 v163, v163
	v_pk_add_f32 v[156:157], v[156:157], v[174:175] op_sel_hi:[1,0]
	v_pk_add_f32 v[158:159], v[158:159], v[174:175] op_sel_hi:[1,0]
	v_pk_add_f32 v[160:161], v[160:161], v[174:175] op_sel_hi:[1,0]
	v_pk_add_f32 v[162:163], v[162:163], v[174:175] op_sel_hi:[1,0]
	v_rcp_f32_e32 v156, v156
	v_rcp_f32_e32 v157, v157
	v_rcp_f32_e32 v158, v158
	v_rcp_f32_e32 v159, v159
	v_rcp_f32_e32 v160, v160
	v_rcp_f32_e32 v161, v161
	v_rcp_f32_e32 v162, v162
	v_rcp_f32_e32 v163, v163
	v_pk_mul_f32 v[156:157], v[108:109], v[156:157]
	v_pk_mul_f32 v[158:159], v[110:111], v[158:159]
	v_pk_mul_f32 v[160:161], v[100:101], v[160:161]
	v_pk_mul_f32 v[162:163], v[102:103], v[162:163]
	v_pk_mul_f32 v[156:157], v[104:105], v[156:157]
	v_pk_mul_f32 v[158:159], v[106:107], v[158:159]
	v_pk_mul_f32 v[160:161], v[96:97], v[160:161]
	v_pk_mul_f32 v[162:163], v[98:99], v[162:163]
	v_cvt_pk_bf16_f32 v168, v156, v157
	v_cvt_pk_bf16_f32 v169, v158, v159
	v_cvt_pk_bf16_f32 v170, v160, v161
	v_cvt_pk_bf16_f32 v171, v162, v163
	global_store_dwordx4 v[144:145], v[168:171], off
	v_lshl_add_u64 v[146:147], v[144:145], 0, s[0:1]
	v_mov_b32_e32 v154, v248
	v_pk_mul_f32 v[92:93], v[92:93], v[154:155] op_sel_hi:[1,0]
	v_pk_mul_f32 v[94:95], v[94:95], v[154:155] op_sel_hi:[1,0]
	v_pk_mul_f32 v[84:85], v[84:85], v[154:155] op_sel_hi:[1,0]
	v_pk_mul_f32 v[86:87], v[86:87], v[154:155] op_sel_hi:[1,0]
	v_pk_mul_f32 v[88:89], v[88:89], v[154:155] op_sel_hi:[1,0]
	v_pk_mul_f32 v[90:91], v[90:91], v[154:155] op_sel_hi:[1,0]
	v_pk_mul_f32 v[80:81], v[80:81], v[154:155] op_sel_hi:[1,0]
	v_pk_mul_f32 v[82:83], v[82:83], v[154:155] op_sel_hi:[1,0]
	v_pk_mul_f32 v[156:157], v[92:93], v[172:173] op_sel_hi:[1,0]
	v_pk_mul_f32 v[158:159], v[94:95], v[172:173] op_sel_hi:[1,0]
	v_pk_mul_f32 v[160:161], v[84:85], v[172:173] op_sel_hi:[1,0]
	v_pk_mul_f32 v[162:163], v[86:87], v[172:173] op_sel_hi:[1,0]
	v_exp_f32_e32 v156, v156
	v_exp_f32_e32 v157, v157
	v_exp_f32_e32 v158, v158
	v_exp_f32_e32 v159, v159
	v_exp_f32_e32 v160, v160
	v_exp_f32_e32 v161, v161
	v_exp_f32_e32 v162, v162
	v_exp_f32_e32 v163, v163
; __device__ __forceinline__ float silu_f(float v) { return v * sigmoid_f(v); }
; __device__ __forceinline__ u32x4 pack8(const f32x4 a, const f32x4 b) { u32x4 w; w.x = cvt_pk_bf16(a[0], a[1]); w.y = cvt_pk_bf16(a[2], a[3]); w.z = cvt_pk_bf16(b[0], b[1]); w.w = cvt_pk_bf16(b[2], b[3]); return w; }
;     __device__ __forceinline__ void operator()(const f32x4 (&acc)[2][2][4][2], const Unit& u, int wr, int wc, int fr_, int fq_) const {
;     ...
;         for (int ai = 0; ai < 2; ++ai)
; #pragma unroll
;             for (int m = 0; m < 4; ++m) { bf16_t* rowp = act + (unsigned)(row0 + ai * HALF + m * 16) * ld + colb;
;                 f32x4 p0, p1; const float rv = 1.0f / sqrtf(ss_read(ss, row0 + ai * HALF + m * 16, fq) * (1.0f / 2048.0f) + 1e-6f);
; #pragma unroll
;                 for (int e = 0; e < 4; ++e) { p0[e] = silu_f(acc[ai][0][m][0][e] * rv) * (acc[ai][1][m][0][e] * rv); p1[e] = silu_f(acc[ai][0][m][1][e] * rv) * (acc[ai][1][m][1][e] * rv); }
;                 *(u32x4*)rowp = pack8(p0, p1); }
	v_pk_add_f32 v[156:157], v[156:157], v[174:175] op_sel_hi:[1,0]
	v_pk_add_f32 v[158:159], v[158:159], v[174:175] op_sel_hi:[1,0]
	v_pk_add_f32 v[160:161], v[160:161], v[174:175] op_sel_hi:[1,0]
	v_pk_add_f32 v[162:163], v[162:163], v[174:175] op_sel_hi:[1,0]
	v_rcp_f32_e32 v156, v156
	v_rcp_f32_e32 v157, v157
	v_rcp_f32_e32 v158, v158
	v_rcp_f32_e32 v159, v159
	v_rcp_f32_e32 v160, v160
	v_rcp_f32_e32 v161, v161
	v_rcp_f32_e32 v162, v162
	v_rcp_f32_e32 v163, v163
	v_pk_mul_f32 v[156:157], v[92:93], v[156:157]
	v_pk_mul_f32 v[158:159], v[94:95], v[158:159]
	v_pk_mul_f32 v[160:161], v[84:85], v[160:161]
	v_pk_mul_f32 v[162:163], v[86:87], v[162:163]
	v_pk_mul_f32 v[156:157], v[88:89], v[156:157]
	v_pk_mul_f32 v[158:159], v[90:91], v[158:159]
	v_pk_mul_f32 v[160:161], v[80:81], v[160:161]
	v_pk_mul_f32 v[162:163], v[82:83], v[162:163]
	v_cvt_pk_bf16_f32 v164, v156, v157
	v_cvt_pk_bf16_f32 v165, v158, v159
	v_cvt_pk_bf16_f32 v166, v160, v161
	v_cvt_pk_bf16_f32 v167, v162, v163
	global_store_dwordx4 v[146:147], v[164:167], off
	v_lshl_add_u64 v[144:145], v[146:147], 0, s[0:1]
	v_mov_b32_e32 v154, v249
	v_pk_mul_f32 v[76:77], v[76:77], v[154:155] op_sel_hi:[1,0]
	v_pk_mul_f32 v[78:79], v[78:79], v[154:155] op_sel_hi:[1,0]
	v_pk_mul_f32 v[68:69], v[68:69], v[154:155] op_sel_hi:[1,0]
	v_pk_mul_f32 v[70:71], v[70:71], v[154:155] op_sel_hi:[1,0]
	v_pk_mul_f32 v[72:73], v[72:73], v[154:155] op_sel_hi:[1,0]
	v_pk_mul_f32 v[74:75], v[74:75], v[154:155] op_sel_hi:[1,0]
	v_pk_mul_f32 v[64:65], v[64:65], v[154:155] op_sel_hi:[1,0]
	v_pk_mul_f32 v[66:67], v[66:67], v[154:155] op_sel_hi:[1,0]
	v_pk_mul_f32 v[156:157], v[76:77], v[172:173] op_sel_hi:[1,0]
	v_pk_mul_f32 v[158:159], v[78:79], v[172:173] op_sel_hi:[1,0]
	v_pk_mul_f32 v[160:161], v[68:69], v[172:173] op_sel_hi:[1,0]
	v_pk_mul_f32 v[162:163], v[70:71], v[172:173] op_sel_hi:[1,0]
	v_exp_f32_e32 v156, v156
	v_exp_f32_e32 v157, v157
	v_exp_f32_e32 v158, v158
	v_exp_f32_e32 v159, v159
	v_exp_f32_e32 v160, v160
	v_exp_f32_e32 v161, v161
	v_exp_f32_e32 v162, v162
	v_exp_f32_e32 v163, v163
	v_pk_add_f32 v[156:157], v[156:157], v[174:175] op_sel_hi:[1,0]
	v_pk_add_f32 v[158:159], v[158:159], v[174:175] op_sel_hi:[1,0]
	v_pk_add_f32 v[160:161], v[160:161], v[174:175] op_sel_hi:[1,0]
	v_pk_add_f32 v[162:163], v[162:163], v[174:175] op_sel_hi:[1,0]
	v_rcp_f32_e32 v156, v156
	v_rcp_f32_e32 v157, v157
	v_rcp_f32_e32 v158, v158
	v_rcp_f32_e32 v159, v159
	v_rcp_f32_e32 v160, v160
	v_rcp_f32_e32 v161, v161
	v_rcp_f32_e32 v162, v162
	v_rcp_f32_e32 v163, v163
	v_pk_mul_f32 v[156:157], v[76:77], v[156:157]
	v_pk_mul_f32 v[158:159], v[78:79], v[158:159]
	v_pk_mul_f32 v[160:161], v[68:69], v[160:161]
	v_pk_mul_f32 v[162:163], v[70:71], v[162:163]
	v_pk_mul_f32 v[156:157], v[72:73], v[156:157]
	v_pk_mul_f32 v[158:159], v[74:75], v[158:159]
	v_pk_mul_f32 v[160:161], v[64:65], v[160:161]
	v_pk_mul_f32 v[162:163], v[66:67], v[162:163]
	v_cvt_pk_bf16_f32 v168, v156, v157
	v_cvt_pk_bf16_f32 v169, v158, v159
	v_cvt_pk_bf16_f32 v170, v160, v161
	v_cvt_pk_bf16_f32 v171, v162, v163
	global_store_dwordx4 v[144:145], v[168:171], off
	s_mov_b32 s0, 0xdc000
	v_lshl_add_u64 v[146:147], v[144:145], 0, s[0:1]
	s_mov_b32 s0, 0x2c000
	v_mov_b32_e32 v154, v250
	v_pk_mul_f32 v[60:61], v[60:61], v[154:155] op_sel_hi:[1,0]
	v_pk_mul_f32 v[62:63], v[62:63], v[154:155] op_sel_hi:[1,0]
	v_pk_mul_f32 v[52:53], v[52:53], v[154:155] op_sel_hi:[1,0]
	v_pk_mul_f32 v[54:55], v[54:55], v[154:155] op_sel_hi:[1,0]
	v_pk_mul_f32 v[56:57], v[56:57], v[154:155] op_sel_hi:[1,0]
	v_pk_mul_f32 v[58:59], v[58:59], v[154:155] op_sel_hi:[1,0]
	v_pk_mul_f32 v[48:49], v[48:49], v[154:155] op_sel_hi:[1,0]
	v_pk_mul_f32 v[50:51], v[50:51], v[154:155] op_sel_hi:[1,0]
	v_pk_mul_f32 v[156:157], v[60:61], v[172:173] op_sel_hi:[1,0]
	v_pk_mul_f32 v[158:159], v[62:63], v[172:173] op_sel_hi:[1,0]
	v_pk_mul_f32 v[160:161], v[52:53], v[172:173] op_sel_hi:[1,0]
	v_pk_mul_f32 v[162:163], v[54:55], v[172:173] op_sel_hi:[1,0]
	v_exp_f32_e32 v156, v156
	v_exp_f32_e32 v157, v157
	v_exp_f32_e32 v158, v158
	v_exp_f32_e32 v159, v159
	v_exp_f32_e32 v160, v160
	v_exp_f32_e32 v161, v161
	v_exp_f32_e32 v162, v162
	v_exp_f32_e32 v163, v163
	v_pk_add_f32 v[156:157], v[156:157], v[174:175] op_sel_hi:[1,0]
	v_pk_add_f32 v[158:159], v[158:159], v[174:175] op_sel_hi:[1,0]
	v_pk_add_f32 v[160:161], v[160:161], v[174:175] op_sel_hi:[1,0]
	v_pk_add_f32 v[162:163], v[162:163], v[174:175] op_sel_hi:[1,0]
	v_rcp_f32_e32 v156, v156
	v_rcp_f32_e32 v157, v157
	v_rcp_f32_e32 v158, v158
	v_rcp_f32_e32 v159, v159
	v_rcp_f32_e32 v160, v160
	v_rcp_f32_e32 v161, v161
	v_rcp_f32_e32 v162, v162
	v_rcp_f32_e32 v163, v163
	v_pk_mul_f32 v[156:157], v[60:61], v[156:157]
	v_pk_mul_f32 v[158:159], v[62:63], v[158:159]
	v_pk_mul_f32 v[160:161], v[52:53], v[160:161]
	v_pk_mul_f32 v[162:163], v[54:55], v[162:163]
	v_pk_mul_f32 v[156:157], v[56:57], v[156:157]
	v_pk_mul_f32 v[158:159], v[58:59], v[158:159]
	v_pk_mul_f32 v[160:161], v[48:49], v[160:161]
	v_pk_mul_f32 v[162:163], v[50:51], v[162:163]
	v_cvt_pk_bf16_f32 v164, v156, v157
	v_cvt_pk_bf16_f32 v165, v158, v159
	v_cvt_pk_bf16_f32 v166, v160, v161
	v_cvt_pk_bf16_f32 v167, v162, v163
	global_store_dwordx4 v[146:147], v[164:167], off
	v_lshl_add_u64 v[144:145], v[146:147], 0, s[0:1]
	v_mov_b32_e32 v154, v251
	v_pk_mul_f32 v[44:45], v[44:45], v[154:155] op_sel_hi:[1,0]
	v_pk_mul_f32 v[46:47], v[46:47], v[154:155] op_sel_hi:[1,0]
	v_pk_mul_f32 v[36:37], v[36:37], v[154:155] op_sel_hi:[1,0]
	v_pk_mul_f32 v[38:39], v[38:39], v[154:155] op_sel_hi:[1,0]
	v_pk_mul_f32 v[40:41], v[40:41], v[154:155] op_sel_hi:[1,0]
	v_pk_mul_f32 v[42:43], v[42:43], v[154:155] op_sel_hi:[1,0]
; __device__ __forceinline__ float silu_f(float v) { return v * sigmoid_f(v); }
; __device__ __forceinline__ u32x4 pack8(const f32x4 a, const f32x4 b) { u32x4 w; w.x = cvt_pk_bf16(a[0], a[1]); w.y = cvt_pk_bf16(a[2], a[3]); w.z = cvt_pk_bf16(b[0], b[1]); w.w = cvt_pk_bf16(b[2], b[3]); return w; }
; #define PG8_BAR __builtin_amdgcn_s_barrier()
;     __device__ __forceinline__ void operator()(const f32x4 (&acc)[2][2][4][2], const Unit& u, int wr, int wc, int fr_, int fq_) const {
;     ...
;         for (int ai = 0; ai < 2; ++ai)
; #pragma unroll
;             for (int m = 0; m < 4; ++m) { bf16_t* rowp = act + (unsigned)(row0 + ai * HALF + m * 16) * ld + colb;
;                 f32x4 p0, p1; const float rv = 1.0f / sqrtf(ss_read(ss, row0 + ai * HALF + m * 16, fq) * (1.0f / 2048.0f) + 1e-6f);
; #pragma unroll
;                 for (int e = 0; e < 4; ++e) { p0[e] = silu_f(acc[ai][0][m][0][e] * rv) * (acc[ai][1][m][0][e] * rv); p1[e] = silu_f(acc[ai][0][m][1][e] * rv) * (acc[ai][1][m][1][e] * rv); }
;                 *(u32x4*)rowp = pack8(p0, p1); }
; template <class Epi, class Sched, bool ALIGN_EPI = false, bool SP2 = false>
; __device__ __forceinline__ void gemm_phase(PG8_LAS unsigned char* lds, const Gemm g, const Sched& S, const Epi& E) {
;     ...
;         if (!has_next) break;
; #pragma unroll
;         for (int a = 0; a < 2; ++a)
; #pragma unroll
;             for (int b = 0; b < 2; ++b)
; #pragma unroll
;                 for (int m = 0; m < 4; ++m)
; #pragma unroll
;                     for (int n = 0; n < 2; ++n) acc[a][b][m][n] = (f32x4){0.f, 0.f, 0.f, 0.f};
;         cur = nxt; cA = nA; cB = nB; ++ui;
;         if constexpr (ALIGN_EPI) { if (wr == 1) PG8_BAR; }
	v_pk_mul_f32 v[32:33], v[32:33], v[154:155] op_sel_hi:[1,0]
	v_pk_mul_f32 v[34:35], v[34:35], v[154:155] op_sel_hi:[1,0]
	v_pk_mul_f32 v[156:157], v[44:45], v[172:173] op_sel_hi:[1,0]
	v_pk_mul_f32 v[158:159], v[46:47], v[172:173] op_sel_hi:[1,0]
	v_pk_mul_f32 v[160:161], v[36:37], v[172:173] op_sel_hi:[1,0]
	v_pk_mul_f32 v[162:163], v[38:39], v[172:173] op_sel_hi:[1,0]
	v_exp_f32_e32 v156, v156
	v_exp_f32_e32 v157, v157
	v_exp_f32_e32 v158, v158
	v_exp_f32_e32 v159, v159
	v_exp_f32_e32 v160, v160
	v_exp_f32_e32 v161, v161
	v_exp_f32_e32 v162, v162
	v_exp_f32_e32 v163, v163
	v_pk_add_f32 v[156:157], v[156:157], v[174:175] op_sel_hi:[1,0]
	v_pk_add_f32 v[158:159], v[158:159], v[174:175] op_sel_hi:[1,0]
	v_pk_add_f32 v[160:161], v[160:161], v[174:175] op_sel_hi:[1,0]
	v_pk_add_f32 v[162:163], v[162:163], v[174:175] op_sel_hi:[1,0]
	v_rcp_f32_e32 v156, v156
	v_rcp_f32_e32 v157, v157
	v_rcp_f32_e32 v158, v158
	v_rcp_f32_e32 v159, v159
	v_rcp_f32_e32 v160, v160
	v_rcp_f32_e32 v161, v161
	v_rcp_f32_e32 v162, v162
	v_rcp_f32_e32 v163, v163
	v_pk_mul_f32 v[156:157], v[44:45], v[156:157]
	v_pk_mul_f32 v[158:159], v[46:47], v[158:159]
	v_pk_mul_f32 v[160:161], v[36:37], v[160:161]
	v_pk_mul_f32 v[162:163], v[38:39], v[162:163]
	v_pk_mul_f32 v[156:157], v[40:41], v[156:157]
	v_pk_mul_f32 v[158:159], v[42:43], v[158:159]
	v_pk_mul_f32 v[160:161], v[32:33], v[160:161]
	v_pk_mul_f32 v[162:163], v[34:35], v[162:163]
	v_cvt_pk_bf16_f32 v168, v156, v157
	v_cvt_pk_bf16_f32 v169, v158, v159
	v_cvt_pk_bf16_f32 v170, v160, v161
	v_cvt_pk_bf16_f32 v171, v162, v163
	global_store_dwordx4 v[144:145], v[168:171], off
	v_lshl_add_u64 v[146:147], v[144:145], 0, s[0:1]
	v_mov_b32_e32 v154, v236
	v_pk_mul_f32 v[28:29], v[28:29], v[154:155] op_sel_hi:[1,0]
	v_pk_mul_f32 v[30:31], v[30:31], v[154:155] op_sel_hi:[1,0]
	v_pk_mul_f32 v[20:21], v[20:21], v[154:155] op_sel_hi:[1,0]
	v_pk_mul_f32 v[22:23], v[22:23], v[154:155] op_sel_hi:[1,0]
	v_pk_mul_f32 v[24:25], v[24:25], v[154:155] op_sel_hi:[1,0]
	v_pk_mul_f32 v[26:27], v[26:27], v[154:155] op_sel_hi:[1,0]
	v_pk_mul_f32 v[16:17], v[16:17], v[154:155] op_sel_hi:[1,0]
	v_pk_mul_f32 v[18:19], v[18:19], v[154:155] op_sel_hi:[1,0]
	v_pk_mul_f32 v[156:157], v[28:29], v[172:173] op_sel_hi:[1,0]
	v_pk_mul_f32 v[158:159], v[30:31], v[172:173] op_sel_hi:[1,0]
	v_pk_mul_f32 v[160:161], v[20:21], v[172:173] op_sel_hi:[1,0]
	v_pk_mul_f32 v[162:163], v[22:23], v[172:173] op_sel_hi:[1,0]
	v_exp_f32_e32 v156, v156
	v_exp_f32_e32 v157, v157
	v_exp_f32_e32 v158, v158
	v_exp_f32_e32 v159, v159
	v_exp_f32_e32 v160, v160
	v_exp_f32_e32 v161, v161
	v_exp_f32_e32 v162, v162
	v_exp_f32_e32 v163, v163
	v_pk_add_f32 v[156:157], v[156:157], v[174:175] op_sel_hi:[1,0]
	v_pk_add_f32 v[158:159], v[158:159], v[174:175] op_sel_hi:[1,0]
	v_pk_add_f32 v[160:161], v[160:161], v[174:175] op_sel_hi:[1,0]
	v_pk_add_f32 v[162:163], v[162:163], v[174:175] op_sel_hi:[1,0]
	v_rcp_f32_e32 v156, v156
	v_rcp_f32_e32 v157, v157
	v_rcp_f32_e32 v158, v158
	v_rcp_f32_e32 v159, v159
	v_rcp_f32_e32 v160, v160
	v_rcp_f32_e32 v161, v161
	v_rcp_f32_e32 v162, v162
	v_rcp_f32_e32 v163, v163
	v_pk_mul_f32 v[156:157], v[28:29], v[156:157]
	v_pk_mul_f32 v[158:159], v[30:31], v[158:159]
	v_pk_mul_f32 v[160:161], v[20:21], v[160:161]
	v_pk_mul_f32 v[162:163], v[22:23], v[162:163]
	v_pk_mul_f32 v[156:157], v[24:25], v[156:157]
	v_pk_mul_f32 v[158:159], v[26:27], v[158:159]
	v_pk_mul_f32 v[160:161], v[16:17], v[160:161]
	v_pk_mul_f32 v[162:163], v[18:19], v[162:163]
	v_cvt_pk_bf16_f32 v164, v156, v157
	v_cvt_pk_bf16_f32 v165, v158, v159
	v_cvt_pk_bf16_f32 v166, v160, v161
	v_cvt_pk_bf16_f32 v167, v162, v163
	global_store_dwordx4 v[146:147], v[164:167], off
	v_lshl_add_u64 v[144:145], v[146:147], 0, s[0:1]
	v_mov_b32_e32 v154, v237
	v_pk_mul_f32 v[12:13], v[12:13], v[154:155] op_sel_hi:[1,0]
	v_pk_mul_f32 v[14:15], v[14:15], v[154:155] op_sel_hi:[1,0]
	v_pk_mul_f32 v[4:5], v[4:5], v[154:155] op_sel_hi:[1,0]
	v_pk_mul_f32 v[6:7], v[6:7], v[154:155] op_sel_hi:[1,0]
	v_pk_mul_f32 v[8:9], v[8:9], v[154:155] op_sel_hi:[1,0]
	v_pk_mul_f32 v[10:11], v[10:11], v[154:155] op_sel_hi:[1,0]
	v_pk_mul_f32 v[0:1], v[0:1], v[154:155] op_sel_hi:[1,0]
	v_pk_mul_f32 v[2:3], v[2:3], v[154:155] op_sel_hi:[1,0]
	v_pk_mul_f32 v[156:157], v[12:13], v[172:173] op_sel_hi:[1,0]
	v_pk_mul_f32 v[158:159], v[14:15], v[172:173] op_sel_hi:[1,0]
	v_pk_mul_f32 v[160:161], v[4:5], v[172:173] op_sel_hi:[1,0]
	v_pk_mul_f32 v[162:163], v[6:7], v[172:173] op_sel_hi:[1,0]
	v_exp_f32_e32 v156, v156
	v_exp_f32_e32 v157, v157
	v_exp_f32_e32 v158, v158
	v_exp_f32_e32 v159, v159
	v_exp_f32_e32 v160, v160
	v_exp_f32_e32 v161, v161
	v_exp_f32_e32 v162, v162
	v_exp_f32_e32 v163, v163
	v_pk_add_f32 v[156:157], v[156:157], v[174:175] op_sel_hi:[1,0]
	v_pk_add_f32 v[158:159], v[158:159], v[174:175] op_sel_hi:[1,0]
	v_pk_add_f32 v[160:161], v[160:161], v[174:175] op_sel_hi:[1,0]
	v_pk_add_f32 v[162:163], v[162:163], v[174:175] op_sel_hi:[1,0]
	v_rcp_f32_e32 v156, v156
	v_rcp_f32_e32 v157, v157
	v_rcp_f32_e32 v158, v158
	v_rcp_f32_e32 v159, v159
	v_rcp_f32_e32 v160, v160
	v_rcp_f32_e32 v161, v161
	v_rcp_f32_e32 v162, v162
	v_rcp_f32_e32 v163, v163
	v_pk_mul_f32 v[156:157], v[12:13], v[156:157]
	v_pk_mul_f32 v[158:159], v[14:15], v[158:159]
	v_pk_mul_f32 v[160:161], v[4:5], v[160:161]
	v_pk_mul_f32 v[162:163], v[6:7], v[162:163]
	v_pk_mul_f32 v[156:157], v[8:9], v[156:157]
	v_pk_mul_f32 v[158:159], v[10:11], v[158:159]
	v_pk_mul_f32 v[160:161], v[0:1], v[160:161]
	v_pk_mul_f32 v[162:163], v[2:3], v[162:163]
	v_cvt_pk_bf16_f32 v168, v156, v157
	v_cvt_pk_bf16_f32 v169, v158, v159
	v_cvt_pk_bf16_f32 v170, v160, v161
	v_cvt_pk_bf16_f32 v171, v162, v163
	global_store_dwordx4 v[144:145], v[168:171], off
	s_mov_b64 s[0:1], -1
	s_andn2_b64 vcc, exec, s[42:43]
	s_cbranch_vccnz .LBB0_726
	s_andn2_b64 vcc, exec, s[4:5]
	s_cbranch_vccnz .LBB0_725
	s_barrier
	s_branch .LBB0_725
